# O1/O2 gemm_stream loops: sumsq packed f32 ops (v_pk_mul/fma/add) split into scalar f32 ops, on top of v31
# baseline (speedup 1.0000x reference)
;     ...
;     auto issue = [&](u32x4 (&ra)[4], u32x4 (&rb)[2], u32x4& rx) {
;       const int idc = l_id < last_id ? l_id : last_id;
;       int mt, nt; if (TMAP == 1) rem_tile(idc, mt, nt); else tile_of(idc, ntn, mt, nt);
;       const bf16_t* A = (l_kt < ktsplit) ? A0 : A1;
;       const int kk = (l_kt < ktsplit) ? l_kt : l_kt - ktsplit;
;       const int arow = mt * 2 * BMH + hh * BMH + srow;
;       const bf16_t* akb = A + kk * kstride + (tid & 7) * 8;
;       const bf16_t* wp = W + (size_t)(nt * 128 + wrow) * K + l_kt * 64 + (tid5 & 7) * 8;
; #pragma unroll
;       for (int i = 0; i < 4; ++i) {
;         int r = arow + 32 * i; r = r < M_ ? r : M_ - 1;
;         ra[i] = *(const u32x4*)(akb + (size_t)r * lda);
;       }
; #pragma unroll
;       for (int i = 0; i < 2; ++i) rb[i] = *(const u32x4*)(wp + (size_t)i * 64 * K);
;       if (TI == 5) rx = *(const u32x4*)(akb + (size_t)(arow - srow + 128) * lda);
;       if (++l_kt == nk) { l_kt = 0; l_id += G; }
;     };
;     auto store = [&](const u32x4 (&ra)[4], const u32x4 (&rb)[2], const u32x4& rx, int buf) {
; #pragma unroll
;       for (int i = 0; i < 4; ++i) {
;         if (RS) ss[i] += sumsq8(__builtin_bit_cast(bf16x8, ra[i]));
;         *(u32x4*)(As + buf * ASTG + i * 4096 + soff) = ra[i];
;       }
; #pragma unroll
;       for (int i = 0; i < 2; ++i) *(u32x4*)(Bs + buf * 16384 + i * 8192 + woff) = rb[i];
;       if (TI == 5) {
;         if (RS) ss[4] += sumsq8(__builtin_bit_cast(bf16x8, rx));
;         if (srow == 0) *(u32x4*)(Ax0 + buf * 128 + ((tid & 7) << 4)) = rx;
;     ...
;     auto compute = [&](int buf) {
;       const unsigned char* Ab = As + buf * ASTG + (wn * 64 + lr) * 128;
;       const unsigned char* Ax = Ax0 + buf * 128;
;       const unsigned char* Bb = Bs + buf * 16384 + (wm * 64 + lr) * 128;
; #pragma unroll
;       for (int ks = 0; ks < 2; ++ks) {
;         if (TI == 5 && ks == 1) __builtin_amdgcn_sched_barrier(0);
;         const int sw = ((ks * 4 + lq) ^ (lr & 7)) << 4;
;         bf16x8 wf[4], xf[TI];
; #pragma unroll
;         for (int i = 0; i < 4; ++i) {
;           wf[i] = *(const bf16x8*)(Bb + i * 2048 + sw);
;           xf[i] = *(const bf16x8*)(Ab + i * 2048 + sw);
;         }
;         if (TI == 5) xf[TI - 1] = *(const bf16x8*)(Ax + ((ks * 4 + lq) << 4));
; #pragma unroll
;         for (int ni = 0; ni < 4; ++ni)
; #pragma unroll
.LBB0_593:
	v_add_u32_e32 v125, v143, v144
	ds_read_b128 v[30:33], v125 offset:32768
	v_add_u32_e32 v130, v142, v144
	ds_read_b128 v[34:37], v130
	ds_read_b128 v[38:41], v125 offset:34816
	ds_read_b128 v[42:45], v130 offset:2048
	s_cmp_lt_i32 s6, 2.0
	s_waitcnt lgkmcnt(1)
	v_mfma_f32_16x16x32_bf16 v[94:97], v[38:41], v[34:37], v[94:97]
	s_cselect_b32 s11, s43, 0
	s_cselect_b32 s12, s42, 0
	v_add_u32_e32 v117, s4, v139
	v_mfma_f32_16x16x32_bf16 v[50:53], v[30:33], v[34:37], v[110:113]
	s_lshl_b32 s4, s6, 6
	s_ashr_i32 s5, s4, 31
	s_lshl_b64 s[4:5], s[4:5], 1
	s_waitcnt lgkmcnt(0)
	v_mfma_f32_16x16x32_bf16 v[54:57], v[30:33], v[42:45], v[106:109]
	s_nop 2
	ds_read_b128 v[106:109], v130 offset:4096
	ds_read_b128 v[110:113], v130 offset:6144
	v_add_u32_e32 v13, v143, v145
	s_add_u32 s12, s12, s4
	s_waitcnt lgkmcnt(1)
	v_mfma_f32_16x16x32_bf16 v[102:105], v[30:33], v[106:109], v[102:105]
	s_addc_u32 s13, s11, s5
	v_mov_b32_e32 v115, v12
	v_add_u32_e32 v131, v142, v145
	s_waitcnt lgkmcnt(0)
	v_mfma_f32_16x16x32_bf16 v[30:33], v[30:33], v[110:113], v[98:101]
	s_mov_b32 s2, 0x20000
	s_mov_b32 s3, 0x30000
	s_add_i32 s35, s9, 1
	v_mfma_f32_16x16x32_bf16 v[90:93], v[38:41], v[42:45], v[90:93]
	ds_read_b128 v[98:101], v125 offset:36864
	s_cmp_lg_u32 s35, 16
	v_mfma_f32_16x16x32_bf16 v[86:89], v[38:41], v[106:109], v[86:89]
	v_mfma_f32_16x16x32_bf16 v[82:85], v[38:41], v[110:113], v[82:85]
	ds_read_b128 v[38:41], v125 offset:38912
	s_waitcnt lgkmcnt(0)
	v_mfma_f32_16x16x32_bf16 v[158:161], v[38:41], v[34:37], v[62:65]
	s_nop 2
	ds_read_b128 v[62:65], v13 offset:32768
	v_mfma_f32_16x16x32_bf16 v[132:135], v[98:101], v[34:37], v[78:81]
	v_min_i32_e32 v34, 0x405f, v117
	v_ashrrev_i32_e32 v35, 31, v34
	v_lshlrev_b64 v[34:35], 11, v[34:35]
	v_mfma_f32_16x16x32_bf16 v[150:153], v[98:101], v[42:45], v[74:77]
	s_nop 2
	v_lshl_add_u64 v[74:75], s[12:13], 0, v[114:115]
	v_mfma_f32_16x16x32_bf16 v[154:157], v[98:101], v[106:109], v[70:73]
	v_lshl_add_u64 v[34:35], v[74:75], 0, v[34:35]
	v_add_co_u32_e32 v34, vcc, s82, v34
	s_nop 0
	v_min_i32_e32 v70, 0x407f, v117
	v_ashrrev_i32_e32 v71, 31, v70
	v_mfma_f32_16x16x32_bf16 v[98:101], v[98:101], v[110:113], v[66:69]
	v_addc_co_u32_e32 v35, vcc, 0, v35, vcc
	v_lshl_add_u32 v76, s10, 7, v138
	s_nop 0
	v_lshlrev_b64 v[66:67], 11, v[70:71]
	v_lshl_add_u64 v[66:67], v[74:75], 0, v[66:67]
	v_mfma_f32_16x16x32_bf16 v[168:171], v[38:41], v[42:45], v[58:61]
	v_ashrrev_i32_e32 v77, 31, v76
	v_mfma_f32_16x16x32_bf16 v[176:179], v[38:41], v[106:109], v[46:49]
	ds_read_b128 v[106:109], v131
	global_load_dwordx4 v[42:45], v[66:67], off
	s_nop 0
	global_load_dwordx4 v[34:37], v[34:35], off
	ds_read_b128 v[78:81], v13 offset:34816
	ds_read_b128 v[202:205], v131 offset:2048
	ds_read_b128 v[206:209], v131 offset:4096
	ds_read_b128 v[210:213], v131 offset:6144
	v_mfma_f32_16x16x32_bf16 v[180:183], v[38:41], v[110:113], v[26:29]
	v_min_i32_e32 v38, 0x403f, v117
	v_ashrrev_i32_e32 v39, 31, v38
	v_lshlrev_b64 v[38:39], 11, v[38:39]
	v_min_i32_e32 v40, 0x401f, v117
	v_lshl_add_u64 v[38:39], v[74:75], 0, v[38:39]
	v_ashrrev_i32_e32 v41, 31, v40
	s_waitcnt lgkmcnt(4)
	v_mfma_f32_16x16x32_bf16 v[26:29], v[62:65], v[106:109], v[50:53]
	v_add_co_u32_e32 v38, vcc, s2, v38
	v_mov_b32_e32 v117, v12
	s_waitcnt lgkmcnt(2)
	v_mfma_f32_16x16x32_bf16 v[46:49], v[62:65], v[202:205], v[54:57]
	v_lshlrev_b64 v[50:51], 11, v[76:77]
	v_addc_co_u32_e32 v39, vcc, 0, v39, vcc
	s_waitcnt lgkmcnt(1)
	v_mfma_f32_16x16x32_bf16 v[58:61], v[62:65], v[206:209], v[102:105]
	v_lshl_add_u64 v[50:51], s[44:45], 0, v[50:51]
	v_lshl_add_u64 v[50:51], v[50:51], 0, s[4:5]
	v_lshl_add_u64 v[50:51], v[50:51], 0, v[116:117]
	s_waitcnt lgkmcnt(0)
	v_mfma_f32_16x16x32_bf16 v[62:65], v[62:65], v[210:213], v[30:33]
	s_waitcnt vmcnt(7)
	v_and_b32_e32 v103, 0xffff0000, v4
	s_waitcnt vmcnt(6)
	v_and_b32_e32 v102, 0xffff0000, v0
	v_mul_f32_e32 v136, v102, v102
	v_mul_f32_e32 v137, v103, v103
	v_lshlrev_b64 v[30:31], 11, v[40:41]
	v_lshl_add_u64 v[30:31], v[74:75], 0, v[30:31]
	v_add_co_u32_e32 v30, vcc, s3, v30
	v_mfma_f32_16x16x32_bf16 v[66:69], v[78:81], v[106:109], v[94:97]
	s_nop 0
	v_addc_co_u32_e32 v31, vcc, 0, v31, vcc
	v_add_co_u32_e32 v52, vcc, s2, v50
	global_load_dwordx4 v[38:41], v[38:39], off
	s_nop 0
	global_load_dwordx4 v[30:33], v[30:31], off
	v_addc_co_u32_e32 v53, vcc, 0, v51, vcc
	ds_read_b128 v[94:97], v13 offset:36864
	ds_read_b128 v[214:217], v13 offset:38912
	global_load_dwordx4 v[54:57], v[50:51], off
	s_nop 0
	global_load_dwordx4 v[50:53], v[52:53], off
	v_mfma_f32_16x16x32_bf16 v[70:73], v[78:81], v[202:205], v[90:93]
	ds_write_b128 v141, v[4:7] offset:16384
	ds_write_b128 v141, v[0:3] offset:20480
	s_waitcnt vmcnt(9)
;     ...
;     auto store = [&](const u32x4 (&ra)[4], const u32x4 (&rb)[2], const u32x4& rx, int buf) {
; #pragma unroll
;       for (int i = 0; i < 4; ++i) {
;         if (RS) ss[i] += sumsq8(__builtin_bit_cast(bf16x8, ra[i]));
;         *(u32x4*)(As + buf * ASTG + i * 4096 + soff) = ra[i];
;       }
; #pragma unroll
;       for (int i = 0; i < 2; ++i) *(u32x4*)(Bs + buf * 16384 + i * 8192 + woff) = rb[i];
;       if (TI == 5) {
;         if (RS) ss[4] += sumsq8(__builtin_bit_cast(bf16x8, rx));
;         if (srow == 0) *(u32x4*)(Ax0 + buf * 128 + ((tid & 7) << 4)) = rx;
;       }
;       if (RS) {
;         if (++st_kt == nk) {
;           st_kt = 0;
; #pragma unroll
;           for (int i = 0; i < TI; ++i) {
;             float t = ss[i];
;             t += __shfl_xor(t, 1); t += __shfl_xor(t, 2); t += __shfl_xor(t, 4);
;             if ((tid & 7) == 0 && i < 4) rsl[srow + 32 * i] = rsqrtf(t * invK + EPS_);
;             ss[i] = 0.f;
;           }
;         }
	ds_write_b128 v141, v[14:17] offset:24576
	v_mfma_f32_16x16x32_bf16 v[74:77], v[78:81], v[206:209], v[86:89]
	s_waitcnt vmcnt(8)
	ds_write_b128 v141, v[8:11] offset:28672
	s_waitcnt vmcnt(7)
	ds_write_b128 v140, v[22:25] offset:49152
	s_waitcnt vmcnt(6)
	ds_write_b128 v140, v[18:21] offset:57344
	v_mfma_f32_16x16x32_bf16 v[78:81], v[78:81], v[210:213], v[82:85]
	s_waitcnt lgkmcnt(7)
	v_mfma_f32_16x16x32_bf16 v[82:85], v[94:97], v[106:109], v[132:135]
	s_nop 2
	v_lshlrev_b32_e32 v135, 16, v4
	v_lshlrev_b32_e32 v134, 16, v0
	v_and_b32_e32 v133, 0xffff0000, v5
	v_mfma_f32_16x16x32_bf16 v[86:89], v[94:97], v[202:205], v[150:153]
	v_lshlrev_b32_e32 v5, 16, v5
	v_lshlrev_b32_e32 v4, 16, v1
	v_and_b32_e32 v132, 0xffff0000, v1
	v_mfma_f32_16x16x32_bf16 v[90:93], v[94:97], v[206:209], v[154:157]
	v_and_b32_e32 v1, 0xffff0000, v15
	v_and_b32_e32 v0, 0xffff0000, v9
	v_mfma_f32_16x16x32_bf16 v[110:113], v[94:97], v[210:213], v[98:101]
	v_fma_f32 v94, v134, v134, v136
	v_fma_f32 v95, v135, v135, v137
	v_fma_f32 v4, v4, v4, v94
	v_fma_f32 v5, v5, v5, v95
	v_lshlrev_b32_e32 v95, 16, v6
	v_fma_f32 v4, v132, v132, v4
	v_fma_f32 v5, v133, v133, v5
	v_lshlrev_b32_e32 v94, 16, v2
	v_fma_f32 v4, v94, v94, v4
	v_fma_f32 v5, v95, v95, v5
	v_and_b32_e32 v99, 0xffff0000, v6
	v_and_b32_e32 v98, 0xffff0000, v2
	v_fma_f32 v4, v98, v98, v4
	v_fma_f32 v5, v99, v99, v5
	v_lshlrev_b32_e32 v133, 16, v7
	v_lshlrev_b32_e32 v132, 16, v3
	v_fma_f32 v4, v132, v132, v4
	v_fma_f32 v5, v133, v133, v5
	v_and_b32_e32 v7, 0xffff0000, v7
	v_and_b32_e32 v6, 0xffff0000, v3
	v_fma_f32 v4, v6, v6, v4
	v_fma_f32 v5, v7, v7, v5
	v_lshlrev_b32_e32 v3, 16, v14
	v_add_f32_e32 v128, v128, v4
	v_add_f32_e32 v129, v129, v5
	v_and_b32_e32 v5, 0xffff0000, v14
	v_and_b32_e32 v4, 0xffff0000, v8
	v_lshlrev_b32_e32 v2, 16, v8
	v_mul_f32_e32 v4, v4, v4
	v_mul_f32_e32 v5, v5, v5
	v_lshlrev_b32_e32 v7, 16, v15
	v_lshlrev_b32_e32 v6, 16, v9
	v_fma_f32 v2, v2, v2, v4
	v_fma_f32 v3, v3, v3, v5
	s_waitcnt lgkmcnt(6)
	v_mfma_f32_16x16x32_bf16 v[102:105], v[214:217], v[106:109], v[158:161]
	v_fma_f32 v2, v6, v6, v2
	v_fma_f32 v3, v7, v7, v3
	v_fma_f32 v0, v0, v0, v2
	v_fma_f32 v1, v1, v1, v3
	v_lshlrev_b32_e32 v3, 16, v16
	v_lshlrev_b32_e32 v2, 16, v10
	v_fma_f32 v0, v2, v2, v0
	v_fma_f32 v1, v3, v3, v1
	v_and_b32_e32 v3, 0xffff0000, v16
	v_and_b32_e32 v2, 0xffff0000, v10
	v_mfma_f32_16x16x32_bf16 v[106:109], v[214:217], v[202:205], v[168:171]
	v_fma_f32 v0, v2, v2, v0
	v_fma_f32 v1, v3, v3, v1
	v_lshlrev_b32_e32 v3, 16, v17
	v_lshlrev_b32_e32 v2, 16, v11
	v_mfma_f32_16x16x32_bf16 v[94:97], v[214:217], v[206:209], v[176:179]
	v_fma_f32 v0, v2, v2, v0
	v_fma_f32 v1, v3, v3, v1
	v_and_b32_e32 v3, 0xffff0000, v17
	v_and_b32_e32 v2, 0xffff0000, v11
	v_mfma_f32_16x16x32_bf16 v[98:101], v[214:217], v[210:213], v[180:183]
	v_fma_f32 v0, v2, v2, v0
	v_fma_f32 v1, v3, v3, v1
	v_add_f32_e32 v126, v126, v0
	v_add_f32_e32 v127, v127, v1
	s_cbranch_scc1 .LBB0_603
	v_and_b32_e32 v1, 64, v191
	v_xor_b32_e32 v0, 1, v191
	v_add_u32_e32 v2, 64, v1
	v_cmp_lt_i32_e32 vcc, v0, v2
	v_xor_b32_e32 v1, 2, v191
	v_xor_b32_e32 v5, 4, v191
	v_cndmask_b32_e32 v0, v191, v0, vcc
	v_lshlrev_b32_e32 v0, 2, v0
	ds_bpermute_b32 v3, v0, v129
	v_cmp_lt_i32_e32 vcc, v1, v2
	s_waitcnt lgkmcnt(0)
	v_add_f32_e32 v3, v129, v3
	v_cndmask_b32_e32 v1, v191, v1, vcc
	v_lshlrev_b32_e32 v1, 2, v1
	ds_bpermute_b32 v4, v1, v3
	v_cmp_lt_i32_e32 vcc, v5, v2
	s_waitcnt lgkmcnt(0)
	v_add_f32_e32 v3, v3, v4
	v_cndmask_b32_e32 v2, v191, v5, vcc
	v_lshlrev_b32_e32 v2, 2, v2
	ds_bpermute_b32 v4, v2, v3
	s_and_saveexec_b64 s[4:5], s[38:39]
	s_cbranch_execz .LBB0_596
	s_waitcnt lgkmcnt(0)
	v_add_f32_e32 v3, v3, v4
	v_fmamk_f32 v3, v3, 0x3a800000, v187
	v_mul_f32_e32 v4, 0x4b800000, v3
	v_cmp_gt_f32_e32 vcc, s33, v3
	s_nop 1
	v_cndmask_b32_e32 v3, v3, v4, vcc
	v_rsq_f32_e32 v3, v3
	s_nop 0
	v_mul_f32_e32 v4, 0x45800000, v3
	v_cndmask_b32_e32 v3, v3, v4, vcc
	ds_write_b32 v146, v3

;     ...
;     auto store = [&](const u32x4 (&ra)[4], const u32x4 (&rb)[2], const u32x4& rx, int buf) {
; #pragma unroll
;       for (int i = 0; i < 4; ++i) {
;         if (RS) ss[i] += sumsq8(__builtin_bit_cast(bf16x8, ra[i]));
;         *(u32x4*)(As + buf * ASTG + i * 4096 + soff) = ra[i];
;       }
; #pragma unroll
;       for (int i = 0; i < 2; ++i) *(u32x4*)(Bs + buf * 16384 + i * 8192 + woff) = rb[i];
;       if (TI == 5) {
;         if (RS) ss[4] += sumsq8(__builtin_bit_cast(bf16x8, rx));
;         if (srow == 0) *(u32x4*)(Ax0 + buf * 128 + ((tid & 7) << 4)) = rx;
;       }
;       if (RS) {
;         if (++st_kt == nk) {
;           st_kt = 0;
; #pragma unroll
;           for (int i = 0; i < TI; ++i) {
;             float t = ss[i];
;             t += __shfl_xor(t, 1); t += __shfl_xor(t, 2); t += __shfl_xor(t, 4);
;             if ((tid & 7) == 0 && i < 4) rsl[srow + 32 * i] = rsqrtf(t * invK + EPS_);
;             ss[i] = 0.f;
;           }
;         }
.LBB0_627:
	s_waitcnt vmcnt(11)
	v_and_b32_e32 v133, 0xffff0000, v42
	s_waitcnt vmcnt(10)
	v_and_b32_e32 v132, 0xffff0000, v34
	v_lshlrev_b32_e32 v131, 16, v42
	v_lshlrev_b32_e32 v130, 16, v34
	v_mul_f32_e32 v132, v132, v132
	v_mul_f32_e32 v133, v133, v133
	ds_write_b128 v141, v[42:45]
	v_fma_f32 v130, v130, v130, v132
	v_fma_f32 v131, v131, v131, v133
	v_lshlrev_b32_e32 v133, 16, v43
	v_lshlrev_b32_e32 v132, 16, v35
	v_fma_f32 v130, v132, v132, v130
	v_fma_f32 v131, v133, v133, v131
	v_and_b32_e32 v43, 0xffff0000, v43
	v_and_b32_e32 v42, 0xffff0000, v35
	v_fma_f32 v42, v42, v42, v130
	v_fma_f32 v43, v43, v43, v131
	v_lshlrev_b32_e32 v131, 16, v44
	v_lshlrev_b32_e32 v130, 16, v36
	v_fma_f32 v42, v130, v130, v42
	v_fma_f32 v43, v131, v131, v43
	v_and_b32_e32 v131, 0xffff0000, v44
	v_and_b32_e32 v130, 0xffff0000, v36
	v_fma_f32 v42, v130, v130, v42
	v_fma_f32 v43, v131, v131, v43
	v_lshlrev_b32_e32 v130, 16, v37
	v_and_b32_e32 v44, 0xffff0000, v37
	ds_write_b128 v141, v[34:37] offset:4096
	s_waitcnt vmcnt(9)
	ds_write_b128 v141, v[38:41] offset:8192
	v_and_b32_e32 v37, 0xffff0000, v38
	s_waitcnt vmcnt(8)
	v_and_b32_e32 v36, 0xffff0000, v30
	v_lshlrev_b32_e32 v35, 16, v38
	v_lshlrev_b32_e32 v34, 16, v30
	v_mul_f32_e32 v36, v36, v36
	v_mul_f32_e32 v37, v37, v37
	v_lshlrev_b32_e32 v131, 16, v45
	v_fma_f32 v34, v34, v34, v36
	v_fma_f32 v35, v35, v35, v37
	v_lshlrev_b32_e32 v37, 16, v39
	v_lshlrev_b32_e32 v36, 16, v31
	v_fma_f32 v34, v36, v36, v34
	v_fma_f32 v35, v37, v37, v35
	v_and_b32_e32 v37, 0xffff0000, v39
	v_and_b32_e32 v36, 0xffff0000, v31
	v_fma_f32 v34, v36, v36, v34
	v_fma_f32 v35, v37, v37, v35
	v_lshlrev_b32_e32 v37, 16, v40
	v_lshlrev_b32_e32 v36, 16, v32
	v_fma_f32 v34, v36, v36, v34
	v_fma_f32 v35, v37, v37, v35
	v_and_b32_e32 v37, 0xffff0000, v40
	v_and_b32_e32 v36, 0xffff0000, v32
	v_fma_f32 v34, v36, v36, v34
	v_fma_f32 v35, v37, v37, v35
	v_lshlrev_b32_e32 v37, 16, v41
	v_lshlrev_b32_e32 v36, 16, v33
	v_fma_f32 v42, v130, v130, v42
	v_fma_f32 v43, v131, v131, v43
	v_and_b32_e32 v45, 0xffff0000, v45
	v_fma_f32 v34, v36, v36, v34
	v_fma_f32 v35, v37, v37, v35
	v_and_b32_e32 v37, 0xffff0000, v41
	v_and_b32_e32 v36, 0xffff0000, v33
	v_fma_f32 v42, v44, v44, v42
	v_fma_f32 v43, v45, v45, v43
	v_fma_f32 v34, v36, v36, v34
	v_fma_f32 v35, v37, v37, v35
	s_add_i32 s9, s35, 1
	v_pk_add_f32 v[128:129], v[42:43], v[128:129]
	v_pk_add_f32 v[126:127], v[34:35], v[126:127]
	s_cmp_lg_u32 s9, 16
	ds_write_b128 v141, v[30:33] offset:12288
	s_waitcnt vmcnt(7)
	ds_write_b128 v140, v[54:57] offset:32768
	s_waitcnt vmcnt(6)
	ds_write_b128 v140, v[50:53] offset:40960
	s_cbranch_scc1 .LBB0_588
	v_and_b32_e32 v30, 64, v191
	v_xor_b32_e32 v13, 1, v191
	v_add_u32_e32 v31, 64, v30
	v_cmp_lt_i32_e32 vcc, v13, v31
	v_xor_b32_e32 v30, 2, v191
	v_xor_b32_e32 v34, 4, v191
	v_cndmask_b32_e32 v13, v191, v13, vcc
	v_lshlrev_b32_e32 v13, 2, v13
	ds_bpermute_b32 v32, v13, v129
	v_cmp_lt_i32_e32 vcc, v30, v31
	s_waitcnt lgkmcnt(0)
	v_add_f32_e32 v32, v129, v32
	v_cndmask_b32_e32 v30, v191, v30, vcc
	v_lshlrev_b32_e32 v30, 2, v30
	ds_bpermute_b32 v33, v30, v32
	v_cmp_lt_i32_e32 vcc, v34, v31
	s_waitcnt lgkmcnt(0)
	v_add_f32_e32 v32, v32, v33
	v_cndmask_b32_e32 v31, v191, v34, vcc
	v_lshlrev_b32_e32 v31, 2, v31
	ds_bpermute_b32 v33, v31, v32
	s_and_saveexec_b64 s[4:5], s[38:39]
	s_cbranch_execz .LBB0_630
	s_waitcnt lgkmcnt(0)
	v_add_f32_e32 v32, v32, v33
	v_fmamk_f32 v32, v32, 0x3a800000, v187
	v_mul_f32_e32 v33, 0x4b800000, v32
	v_cmp_gt_f32_e32 vcc, s33, v32
	s_nop 1
	v_cndmask_b32_e32 v32, v32, v33, vcc
	v_rsq_f32_e32 v32, v32
	s_nop 0
	v_mul_f32_e32 v33, 0x45800000, v32
	v_cndmask_b32_e32 v32, v32, v33, vcc
	ds_write_b32 v146, v32

;     ...
;     auto issue = [&](u32x4 (&ra)[4], u32x4 (&rb)[2], u32x4& rx) {
;       const int idc = l_id < last_id ? l_id : last_id;
;       int mt, nt; if (TMAP == 1) rem_tile(idc, mt, nt); else tile_of(idc, ntn, mt, nt);
;       const bf16_t* A = (l_kt < ktsplit) ? A0 : A1;
;       const int kk = (l_kt < ktsplit) ? l_kt : l_kt - ktsplit;
;       const int arow = mt * 2 * BMH + hh * BMH + srow;
;       const bf16_t* akb = A + kk * kstride + (tid & 7) * 8;
;       const bf16_t* wp = W + (size_t)(nt * 128 + wrow) * K + l_kt * 64 + (tid5 & 7) * 8;
; #pragma unroll
;       for (int i = 0; i < 4; ++i) {
;         int r = arow + 32 * i; r = r < M_ ? r : M_ - 1;
;         ra[i] = *(const u32x4*)(akb + (size_t)r * lda);
;       }
; #pragma unroll
;       for (int i = 0; i < 2; ++i) rb[i] = *(const u32x4*)(wp + (size_t)i * 64 * K);
;       if (TI == 5) rx = *(const u32x4*)(akb + (size_t)(arow - srow + 128) * lda);
;       if (++l_kt == nk) { l_kt = 0; l_id += G; }
;     };
;     auto store = [&](const u32x4 (&ra)[4], const u32x4 (&rb)[2], const u32x4& rx, int buf) {
; #pragma unroll
;       for (int i = 0; i < 4; ++i) {
;         if (RS) ss[i] += sumsq8(__builtin_bit_cast(bf16x8, ra[i]));
;         *(u32x4*)(As + buf * ASTG + i * 4096 + soff) = ra[i];
;       }
; #pragma unroll
;       for (int i = 0; i < 2; ++i) *(u32x4*)(Bs + buf * 16384 + i * 8192 + woff) = rb[i];
;       if (TI == 5) {
;         if (RS) ss[4] += sumsq8(__builtin_bit_cast(bf16x8, rx));
;         if (srow == 0) *(u32x4*)(Ax0 + buf * 128 + ((tid & 7) << 4)) = rx;
;     ...
;     auto compute = [&](int buf) {
;       const unsigned char* Ab = As + buf * ASTG + (wn * 64 + lr) * 128;
;       const unsigned char* Ax = Ax0 + buf * 128;
;       const unsigned char* Bb = Bs + buf * 16384 + (wm * 64 + lr) * 128;
; #pragma unroll
;       for (int ks = 0; ks < 2; ++ks) {
;         if (TI == 5 && ks == 1) __builtin_amdgcn_sched_barrier(0);
;         const int sw = ((ks * 4 + lq) ^ (lr & 7)) << 4;
;         bf16x8 wf[4], xf[TI];
; #pragma unroll
;         for (int i = 0; i < 4; ++i) {
;           wf[i] = *(const bf16x8*)(Bb + i * 2048 + sw);
;           xf[i] = *(const bf16x8*)(Ab + i * 2048 + sw);
;         }
;         if (TI == 5) xf[TI - 1] = *(const bf16x8*)(Ax + ((ks * 4 + lq) << 4));
; #pragma unroll
;         for (int ni = 0; ni < 4; ++ni)
; #pragma unroll
.LBB0_702:
	v_add_u32_e32 v119, v133, v134
	ds_read_b128 v[30:33], v119 offset:32768
	v_add_u32_e32 v124, v132, v134
	ds_read_b128 v[34:37], v124
	ds_read_b128 v[38:41], v119 offset:34816
	ds_read_b128 v[42:45], v124 offset:2048
	s_cmp_lt_i32 s10, 2.0
	s_waitcnt lgkmcnt(1)
	v_mfma_f32_16x16x32_bf16 v[94:97], v[38:41], v[34:37], v[94:97]
	s_cselect_b32 s47, s5, 0
	s_cselect_b32 s46, s4, 0
	v_add_u32_e32 v117, s12, v129
	v_mfma_f32_16x16x32_bf16 v[50:53], v[30:33], v[34:37], v[110:113]
	s_lshl_b32 s12, s10, 6
	s_ashr_i32 s13, s12, 31
	s_lshl_b64 s[12:13], s[12:13], 1
	s_waitcnt lgkmcnt(0)
	v_mfma_f32_16x16x32_bf16 v[54:57], v[30:33], v[42:45], v[106:109]
	s_nop 2
	ds_read_b128 v[106:109], v124 offset:4096
	ds_read_b128 v[110:113], v124 offset:6144
	v_add_u32_e32 v13, v133, v135
	s_add_u32 s46, s46, s12
	s_waitcnt lgkmcnt(1)
	v_mfma_f32_16x16x32_bf16 v[102:105], v[30:33], v[106:109], v[102:105]
	s_addc_u32 s47, s47, s13
	v_mov_b32_e32 v115, v12
	s_mov_b32 s3, 0x8000
	s_waitcnt lgkmcnt(0)
	v_mfma_f32_16x16x32_bf16 v[30:33], v[30:33], v[110:113], v[98:101]
	v_add_u32_e32 v125, v132, v135
	s_waitcnt vmcnt(5)
	v_and_b32_e32 v127, 0xffff0000, v5
	s_waitcnt vmcnt(4)
	v_and_b32_e32 v126, 0xffff0000, v1
	v_mfma_f32_16x16x32_bf16 v[90:93], v[38:41], v[42:45], v[90:93]
	ds_read_b128 v[98:101], v119 offset:36864
	v_mfma_f32_16x16x32_bf16 v[86:89], v[38:41], v[106:109], v[86:89]
	v_mfma_f32_16x16x32_bf16 v[82:85], v[38:41], v[110:113], v[82:85]
	ds_read_b128 v[38:41], v119 offset:38912
	s_waitcnt lgkmcnt(0)
	v_mfma_f32_16x16x32_bf16 v[152:155], v[38:41], v[34:37], v[62:65]
	s_nop 2
	ds_read_b128 v[62:65], v13 offset:32768
	v_mfma_f32_16x16x32_bf16 v[140:143], v[98:101], v[34:37], v[78:81]
	v_min_i32_e32 v34, 0x405f, v117
	v_ashrrev_i32_e32 v35, 31, v34
	v_lshlrev_b64 v[34:35], 10, v[34:35]
	v_mfma_f32_16x16x32_bf16 v[144:147], v[98:101], v[42:45], v[74:77]
	s_nop 2
	v_lshl_add_u64 v[74:75], s[46:47], 0, v[114:115]
	v_mfma_f32_16x16x32_bf16 v[148:151], v[98:101], v[106:109], v[70:73]
	v_lshl_add_u64 v[34:35], v[74:75], 0, v[34:35]
	v_add_co_u32_e32 v34, vcc, s3, v34
	s_nop 0
	v_min_i32_e32 v70, 0x407f, v117
	v_ashrrev_i32_e32 v71, 31, v70
	v_mfma_f32_16x16x32_bf16 v[98:101], v[98:101], v[110:113], v[66:69]
	v_addc_co_u32_e32 v35, vcc, 0, v35, vcc
	v_lshl_add_u32 v76, s44, 7, v128
	s_nop 0
	v_lshlrev_b64 v[66:67], 10, v[70:71]
	v_lshl_add_u64 v[66:67], v[74:75], 0, v[66:67]
	v_mfma_f32_16x16x32_bf16 v[156:159], v[38:41], v[42:45], v[58:61]
	v_ashrrev_i32_e32 v77, 31, v76
	s_mov_b32 s44, 0x10000
	s_mov_b32 s3, 0x18000
	v_mfma_f32_16x16x32_bf16 v[160:163], v[38:41], v[106:109], v[46:49]
	ds_read_b128 v[106:109], v125
	global_load_dwordx4 v[42:45], v[66:67], off
	s_nop 0
	global_load_dwordx4 v[34:37], v[34:35], off
	ds_read_b128 v[78:81], v13 offset:34816
	ds_read_b128 v[176:179], v125 offset:2048
	ds_read_b128 v[180:183], v125 offset:4096
	ds_read_b128 v[202:205], v125 offset:6144
	v_mfma_f32_16x16x32_bf16 v[168:171], v[38:41], v[110:113], v[26:29]
	v_min_i32_e32 v38, 0x403f, v117
	v_ashrrev_i32_e32 v39, 31, v38
	v_lshlrev_b64 v[38:39], 10, v[38:39]
	v_min_i32_e32 v40, 0x401f, v117
	v_lshl_add_u64 v[38:39], v[74:75], 0, v[38:39]
	v_ashrrev_i32_e32 v41, 31, v40
	s_waitcnt lgkmcnt(4)
	v_mfma_f32_16x16x32_bf16 v[26:29], v[62:65], v[106:109], v[50:53]
	v_add_co_u32_e32 v38, vcc, s44, v38
	v_mov_b32_e32 v117, v12
	s_waitcnt lgkmcnt(2)
	v_mfma_f32_16x16x32_bf16 v[46:49], v[62:65], v[176:179], v[54:57]
	v_lshlrev_b64 v[50:51], 10, v[76:77]
	v_addc_co_u32_e32 v39, vcc, 0, v39, vcc
	s_waitcnt lgkmcnt(1)
	v_mfma_f32_16x16x32_bf16 v[58:61], v[62:65], v[180:183], v[102:105]
	v_lshl_add_u64 v[50:51], s[6:7], 0, v[50:51]
	v_lshl_add_u64 v[50:51], v[50:51], 0, s[12:13]
	v_lshl_add_u64 v[50:51], v[50:51], 0, v[116:117]
	s_waitcnt lgkmcnt(0)
	v_mfma_f32_16x16x32_bf16 v[62:65], v[62:65], v[202:205], v[30:33]
	v_and_b32_e32 v103, 0xffff0000, v4
	v_and_b32_e32 v102, 0xffff0000, v0
	s_add_i32 s47, s45, 1
	v_lshlrev_b64 v[30:31], 10, v[40:41]
	v_lshl_add_u64 v[30:31], v[74:75], 0, v[30:31]
	v_add_co_u32_e32 v30, vcc, s3, v30
	v_mfma_f32_16x16x32_bf16 v[66:69], v[78:81], v[106:109], v[94:97]
	s_nop 0
	v_addc_co_u32_e32 v31, vcc, 0, v31, vcc
	v_add_co_u32_e32 v52, vcc, s44, v50
	global_load_dwordx4 v[38:41], v[38:39], off
	s_nop 0
	global_load_dwordx4 v[30:33], v[30:31], off
	v_addc_co_u32_e32 v53, vcc, 0, v51, vcc
	ds_read_b128 v[94:97], v13 offset:36864
	ds_read_b128 v[206:209], v13 offset:38912
	global_load_dwordx4 v[54:57], v[50:51], off
	s_nop 0
	global_load_dwordx4 v[50:53], v[52:53], off
	v_mfma_f32_16x16x32_bf16 v[70:73], v[78:81], v[176:179], v[90:93]
	ds_write_b128 v131, v[4:7] offset:16384
	v_lshlrev_b32_e32 v5, 16, v5
	ds_write_b128 v131, v[0:3] offset:20480
	v_mfma_f32_16x16x32_bf16 v[74:77], v[78:81], v[180:183], v[86:89]
	s_cmp_lg_u32 s47, 8
	s_waitcnt vmcnt(9)
;     ...
;     auto store = [&](const u32x4 (&ra)[4], const u32x4 (&rb)[2], const u32x4& rx, int buf) {
; #pragma unroll
;       for (int i = 0; i < 4; ++i) {
;         if (RS) ss[i] += sumsq8(__builtin_bit_cast(bf16x8, ra[i]));
;         *(u32x4*)(As + buf * ASTG + i * 4096 + soff) = ra[i];
;       }
; #pragma unroll
;       for (int i = 0; i < 2; ++i) *(u32x4*)(Bs + buf * 16384 + i * 8192 + woff) = rb[i];
;       if (TI == 5) {
;         if (RS) ss[4] += sumsq8(__builtin_bit_cast(bf16x8, rx));
;         if (srow == 0) *(u32x4*)(Ax0 + buf * 128 + ((tid & 7) << 4)) = rx;
;       }
;       if (RS) {
;         if (++st_kt == nk) {
;           st_kt = 0;
; #pragma unroll
;           for (int i = 0; i < TI; ++i) {
;             float t = ss[i];
;             t += __shfl_xor(t, 1); t += __shfl_xor(t, 2); t += __shfl_xor(t, 4);
;             if ((tid & 7) == 0 && i < 4) rsl[srow + 32 * i] = rsqrtf(t * invK + EPS_);
;             ss[i] = 0.f;
;           }
;         }
	ds_write_b128 v131, v[14:17] offset:24576
	s_waitcnt vmcnt(8)
	ds_write_b128 v131, v[8:11] offset:28672
	s_waitcnt vmcnt(7)
	ds_write_b128 v130, v[22:25] offset:49152
	v_mfma_f32_16x16x32_bf16 v[78:81], v[78:81], v[202:205], v[82:85]
	s_waitcnt vmcnt(6)
	ds_write_b128 v130, v[18:21] offset:57344
	s_waitcnt lgkmcnt(7)
	v_mfma_f32_16x16x32_bf16 v[82:85], v[94:97], v[106:109], v[140:143]
	s_nop 2
	v_lshlrev_b32_e32 v141, 16, v4
	v_lshlrev_b32_e32 v140, 16, v0
	v_mul_f32_e32 v142, v102, v102
	v_mul_f32_e32 v143, v103, v103
	v_mfma_f32_16x16x32_bf16 v[86:89], v[94:97], v[176:179], v[144:147]
	v_lshlrev_b32_e32 v4, 16, v1
	v_and_b32_e32 v1, 0xffff0000, v15
	v_and_b32_e32 v0, 0xffff0000, v9
	v_mfma_f32_16x16x32_bf16 v[90:93], v[94:97], v[180:183], v[148:151]
	v_mfma_f32_16x16x32_bf16 v[110:113], v[94:97], v[202:205], v[98:101]
	v_fma_f32 v94, v140, v140, v142
	v_fma_f32 v95, v141, v141, v143
	v_fma_f32 v4, v4, v4, v94
	v_fma_f32 v5, v5, v5, v95
	v_lshlrev_b32_e32 v95, 16, v6
	v_fma_f32 v4, v126, v126, v4
	v_fma_f32 v5, v127, v127, v5
	v_lshlrev_b32_e32 v94, 16, v2
	v_fma_f32 v4, v94, v94, v4
	v_fma_f32 v5, v95, v95, v5
	v_and_b32_e32 v99, 0xffff0000, v6
	v_and_b32_e32 v98, 0xffff0000, v2
	v_fma_f32 v4, v98, v98, v4
	v_fma_f32 v5, v99, v99, v5
	v_lshlrev_b32_e32 v127, 16, v7
	v_lshlrev_b32_e32 v126, 16, v3
	v_fma_f32 v4, v126, v126, v4
	v_fma_f32 v5, v127, v127, v5
	v_and_b32_e32 v7, 0xffff0000, v7
	v_and_b32_e32 v6, 0xffff0000, v3
	v_fma_f32 v4, v6, v6, v4
	v_fma_f32 v5, v7, v7, v5
	v_lshlrev_b32_e32 v3, 16, v14
	v_add_f32_e32 v122, v122, v4
	v_add_f32_e32 v123, v123, v5
	v_and_b32_e32 v5, 0xffff0000, v14
	v_and_b32_e32 v4, 0xffff0000, v8
	v_lshlrev_b32_e32 v2, 16, v8
	v_mul_f32_e32 v4, v4, v4
	v_mul_f32_e32 v5, v5, v5
	v_lshlrev_b32_e32 v7, 16, v15
	v_lshlrev_b32_e32 v6, 16, v9
	v_fma_f32 v2, v2, v2, v4
	v_fma_f32 v3, v3, v3, v5
	s_waitcnt lgkmcnt(6)
	v_mfma_f32_16x16x32_bf16 v[102:105], v[206:209], v[106:109], v[152:155]
	v_fma_f32 v2, v6, v6, v2
	v_fma_f32 v3, v7, v7, v3
	v_fma_f32 v0, v0, v0, v2
	v_fma_f32 v1, v1, v1, v3
	v_lshlrev_b32_e32 v3, 16, v16
	v_lshlrev_b32_e32 v2, 16, v10
	v_fma_f32 v0, v2, v2, v0
	v_fma_f32 v1, v3, v3, v1
	v_and_b32_e32 v3, 0xffff0000, v16
	v_and_b32_e32 v2, 0xffff0000, v10
	v_mfma_f32_16x16x32_bf16 v[106:109], v[206:209], v[176:179], v[156:159]
	v_fma_f32 v0, v2, v2, v0
	v_fma_f32 v1, v3, v3, v1
	v_lshlrev_b32_e32 v3, 16, v17
	v_lshlrev_b32_e32 v2, 16, v11
	v_mfma_f32_16x16x32_bf16 v[94:97], v[206:209], v[180:183], v[160:163]
	v_fma_f32 v0, v2, v2, v0
	v_fma_f32 v1, v3, v3, v1
	v_and_b32_e32 v3, 0xffff0000, v17
	v_and_b32_e32 v2, 0xffff0000, v11
	v_mfma_f32_16x16x32_bf16 v[98:101], v[206:209], v[202:205], v[168:171]
	v_fma_f32 v0, v2, v2, v0
	v_fma_f32 v1, v3, v3, v1
	v_add_f32_e32 v120, v120, v0
	v_add_f32_e32 v121, v121, v1
	s_cbranch_scc1 .LBB0_712
	v_and_b32_e32 v1, 64, v191
	v_xor_b32_e32 v0, 1, v191
	v_add_u32_e32 v2, 64, v1
	v_cmp_lt_i32_e32 vcc, v0, v2
	v_xor_b32_e32 v1, 2, v191
	v_xor_b32_e32 v5, 4, v191
	v_cndmask_b32_e32 v0, v191, v0, vcc
	v_lshlrev_b32_e32 v0, 2, v0
	ds_bpermute_b32 v3, v0, v123
	v_cmp_lt_i32_e32 vcc, v1, v2
	s_waitcnt lgkmcnt(0)
	v_add_f32_e32 v3, v123, v3
	v_cndmask_b32_e32 v1, v191, v1, vcc
	v_lshlrev_b32_e32 v1, 2, v1
	ds_bpermute_b32 v4, v1, v3
	v_cmp_lt_i32_e32 vcc, v5, v2
	s_waitcnt lgkmcnt(0)
	v_add_f32_e32 v3, v3, v4
	v_cndmask_b32_e32 v2, v191, v5, vcc
	v_lshlrev_b32_e32 v2, 2, v2
	ds_bpermute_b32 v4, v2, v3
	s_and_saveexec_b64 s[12:13], s[38:39]
	s_cbranch_execz .LBB0_705
	s_waitcnt lgkmcnt(0)
	v_add_f32_e32 v3, v3, v4
	v_fmamk_f32 v3, v3, 0x3b000000, v187
	v_mul_f32_e32 v4, 0x4b800000, v3
	v_cmp_gt_f32_e32 vcc, s33, v3
	s_nop 1
	v_cndmask_b32_e32 v3, v3, v4, vcc
	v_rsq_f32_e32 v3, v3
	s_nop 0
	v_mul_f32_e32 v4, 0x45800000, v3
	v_cndmask_b32_e32 v3, v3, v4, vcc
	ds_write_b32 v136, v3

;     ...
;     auto store = [&](const u32x4 (&ra)[4], const u32x4 (&rb)[2], const u32x4& rx, int buf) {
; #pragma unroll
;       for (int i = 0; i < 4; ++i) {
;         if (RS) ss[i] += sumsq8(__builtin_bit_cast(bf16x8, ra[i]));
;         *(u32x4*)(As + buf * ASTG + i * 4096 + soff) = ra[i];
;       }
; #pragma unroll
;       for (int i = 0; i < 2; ++i) *(u32x4*)(Bs + buf * 16384 + i * 8192 + woff) = rb[i];
;       if (TI == 5) {
;         if (RS) ss[4] += sumsq8(__builtin_bit_cast(bf16x8, rx));
;         if (srow == 0) *(u32x4*)(Ax0 + buf * 128 + ((tid & 7) << 4)) = rx;
;       }
;       if (RS) {
;         if (++st_kt == nk) {
;           st_kt = 0;
; #pragma unroll
;           for (int i = 0; i < TI; ++i) {
;             float t = ss[i];
;             t += __shfl_xor(t, 1); t += __shfl_xor(t, 2); t += __shfl_xor(t, 4);
;             if ((tid & 7) == 0 && i < 4) rsl[srow + 32 * i] = rsqrtf(t * invK + EPS_);
;             ss[i] = 0.f;
;           }
;         }
;       }
.LBB0_722:
	s_waitcnt vmcnt(11)
	v_and_b32_e32 v127, 0xffff0000, v42
	s_waitcnt vmcnt(10)
	v_and_b32_e32 v126, 0xffff0000, v34
	v_lshlrev_b32_e32 v125, 16, v42
	v_lshlrev_b32_e32 v124, 16, v34
	v_mul_f32_e32 v126, v126, v126
	v_mul_f32_e32 v127, v127, v127
	ds_write_b128 v131, v[42:45]
	v_fma_f32 v124, v124, v124, v126
	v_fma_f32 v125, v125, v125, v127
	v_lshlrev_b32_e32 v127, 16, v43
	v_lshlrev_b32_e32 v126, 16, v35
	v_fma_f32 v124, v126, v126, v124
	v_fma_f32 v125, v127, v127, v125
	v_and_b32_e32 v43, 0xffff0000, v43
	v_and_b32_e32 v42, 0xffff0000, v35
	v_fma_f32 v42, v42, v42, v124
	v_fma_f32 v43, v43, v43, v125
	v_lshlrev_b32_e32 v125, 16, v44
	v_lshlrev_b32_e32 v124, 16, v36
	v_fma_f32 v42, v124, v124, v42
	v_fma_f32 v43, v125, v125, v43
	v_and_b32_e32 v125, 0xffff0000, v44
	v_and_b32_e32 v124, 0xffff0000, v36
	v_fma_f32 v42, v124, v124, v42
	v_fma_f32 v43, v125, v125, v43
	v_lshlrev_b32_e32 v124, 16, v37
	v_and_b32_e32 v44, 0xffff0000, v37
	ds_write_b128 v131, v[34:37] offset:4096
	s_waitcnt vmcnt(9)
	ds_write_b128 v131, v[38:41] offset:8192
	v_and_b32_e32 v37, 0xffff0000, v38
	s_waitcnt vmcnt(8)
	v_and_b32_e32 v36, 0xffff0000, v30
	v_lshlrev_b32_e32 v35, 16, v38
	v_lshlrev_b32_e32 v34, 16, v30
	v_mul_f32_e32 v36, v36, v36
	v_mul_f32_e32 v37, v37, v37
	v_lshlrev_b32_e32 v125, 16, v45
	v_fma_f32 v34, v34, v34, v36
	v_fma_f32 v35, v35, v35, v37
	v_lshlrev_b32_e32 v37, 16, v39
	v_lshlrev_b32_e32 v36, 16, v31
	v_fma_f32 v34, v36, v36, v34
	v_fma_f32 v35, v37, v37, v35
	v_and_b32_e32 v37, 0xffff0000, v39
	v_and_b32_e32 v36, 0xffff0000, v31
	v_fma_f32 v34, v36, v36, v34
	v_fma_f32 v35, v37, v37, v35
	v_lshlrev_b32_e32 v37, 16, v40
	v_lshlrev_b32_e32 v36, 16, v32
	v_fma_f32 v34, v36, v36, v34
	v_fma_f32 v35, v37, v37, v35
	v_and_b32_e32 v37, 0xffff0000, v40
	v_and_b32_e32 v36, 0xffff0000, v32
	v_fma_f32 v34, v36, v36, v34
	v_fma_f32 v35, v37, v37, v35
	v_lshlrev_b32_e32 v37, 16, v41
	v_lshlrev_b32_e32 v36, 16, v33
	v_fma_f32 v42, v124, v124, v42
	v_fma_f32 v43, v125, v125, v43
	v_and_b32_e32 v45, 0xffff0000, v45
	v_fma_f32 v34, v36, v36, v34
	v_fma_f32 v35, v37, v37, v35
	v_and_b32_e32 v37, 0xffff0000, v41
	v_and_b32_e32 v36, 0xffff0000, v33
	v_fma_f32 v42, v44, v44, v42
	v_fma_f32 v43, v45, v45, v43
	v_fma_f32 v34, v36, v36, v34
	v_fma_f32 v35, v37, v37, v35
	s_add_i32 s45, s47, 1
	v_pk_add_f32 v[122:123], v[42:43], v[122:123]
	v_pk_add_f32 v[120:121], v[34:35], v[120:121]
	s_cmp_lg_u32 s45, 8
	ds_write_b128 v131, v[30:33] offset:12288
	s_waitcnt vmcnt(7)
	ds_write_b128 v130, v[54:57] offset:32768
	s_waitcnt vmcnt(6)
	ds_write_b128 v130, v[50:53] offset:40960
	s_cbranch_scc1 .LBB0_697
	v_and_b32_e32 v30, 64, v191
	v_xor_b32_e32 v13, 1, v191
	v_add_u32_e32 v31, 64, v30
	v_cmp_lt_i32_e32 vcc, v13, v31
	v_xor_b32_e32 v30, 2, v191
	v_xor_b32_e32 v34, 4, v191
	v_cndmask_b32_e32 v13, v191, v13, vcc
	v_lshlrev_b32_e32 v13, 2, v13
	ds_bpermute_b32 v32, v13, v123
	v_cmp_lt_i32_e32 vcc, v30, v31
	s_waitcnt lgkmcnt(0)
	v_add_f32_e32 v32, v123, v32
	v_cndmask_b32_e32 v30, v191, v30, vcc
	v_lshlrev_b32_e32 v30, 2, v30
	ds_bpermute_b32 v33, v30, v32
	v_cmp_lt_i32_e32 vcc, v34, v31
	s_waitcnt lgkmcnt(0)
	v_add_f32_e32 v32, v32, v33
	v_cndmask_b32_e32 v31, v191, v34, vcc
	v_lshlrev_b32_e32 v31, 2, v31
	ds_bpermute_b32 v33, v31, v32
	s_and_saveexec_b64 s[12:13], s[38:39]
	s_cbranch_execz .LBB0_725
	s_waitcnt lgkmcnt(0)
	v_add_f32_e32 v32, v32, v33
	v_fmamk_f32 v32, v32, 0x3b000000, v187
	v_mul_f32_e32 v33, 0x4b800000, v32
	v_cmp_gt_f32_e32 vcc, s33, v32
	s_nop 1
	v_cndmask_b32_e32 v32, v32, v33, vcc
	v_rsq_f32_e32 v32, v32
	s_nop 0
	v_mul_f32_e32 v33, 0x45800000, v32
	v_cndmask_b32_e32 v32, v32, v33, vcc
	ds_write_b32 v136, v32

; #define MFMA16(a, b, c) __builtin_amdgcn_mfma_f32_16x16x32_bf16((a), (b), (c), 0, 0, 0)
;     ...
;     auto issue = [&](u32x4 (&ra)[4], u32x4 (&rb)[2], u32x4& rx) {
;       const int idc = l_id < last_id ? l_id : last_id;
;       int mt, nt; if (TMAP == 1) rem_tile(idc, mt, nt); else tile_of(idc, ntn, mt, nt);
;       const bf16_t* A = (l_kt < ktsplit) ? A0 : A1;
;       const int kk = (l_kt < ktsplit) ? l_kt : l_kt - ktsplit;
;       const int arow = mt * 2 * BMH + hh * BMH + srow;
;       const bf16_t* akb = A + kk * kstride + (tid & 7) * 8;
;       const bf16_t* wp = W + (size_t)(nt * 128 + wrow) * K + l_kt * 64 + (tid5 & 7) * 8;
; #pragma unroll
;       for (int i = 0; i < 4; ++i) {
;         int r = arow + 32 * i; r = r < M_ ? r : M_ - 1;
;         ra[i] = *(const u32x4*)(akb + (size_t)r * lda);
;       }
; #pragma unroll
;       for (int i = 0; i < 2; ++i) rb[i] = *(const u32x4*)(wp + (size_t)i * 64 * K);
;       if (TI == 5) rx = *(const u32x4*)(akb + (size_t)(arow - srow + 128) * lda);
;       if (++l_kt == nk) { l_kt = 0; l_id += G; }
;     };
;     ...
;     auto compute = [&](int buf) {
;       const unsigned char* Ab = As + buf * ASTG + (wn * 64 + lr) * 128;
;       const unsigned char* Ax = Ax0 + buf * 128;
;       const unsigned char* Bb = Bs + buf * 16384 + (wm * 64 + lr) * 128;
; #pragma unroll
;       for (int ks = 0; ks < 2; ++ks) {
;         if (TI == 5 && ks == 1) __builtin_amdgcn_sched_barrier(0);
;         const int sw = ((ks * 4 + lq) ^ (lr & 7)) << 4;
;         bf16x8 wf[4], xf[TI];
; #pragma unroll
;         for (int i = 0; i < 4; ++i) {
;           wf[i] = *(const bf16x8*)(Bb + i * 2048 + sw);
;           xf[i] = *(const bf16x8*)(Ab + i * 2048 + sw);
;         }
;         if (TI == 5) xf[TI - 1] = *(const bf16x8*)(Ax + ((ks * 4 + lq) << 4));
; #pragma unroll
;         for (int ni = 0; ni < 4; ++ni)
; #pragma unroll
;           for (int ti = 0; ti < 4; ++ti) acc[ni][ti] = MFMA16(wf[ni], xf[ti], acc[ni][ti]);
;         if (TI == 5) {
;           if (wn == 0) { acc[0][TI - 1] = MFMA16(wf[0], xf[TI - 1], acc[0][TI - 1]); acc[1][TI - 1] = MFMA16(wf[1], xf[TI - 1], acc[1][TI - 1]); }
;           else { acc[2][TI - 1] = MFMA16(wf[2], xf[TI - 1], acc[2][TI - 1]); acc[3][TI - 1] = MFMA16(wf[3], xf[TI - 1], acc[3][TI - 1]); }
;         }
;       }
;     };
.LBB0_750:
	v_add_u32_e32 v121, v139, v140
	ds_read_b128 v[26:29], v121 offset:32768
	v_add_u32_e32 v126, v138, v140
	ds_read_b128 v[30:33], v126
	ds_read_b128 v[34:37], v121 offset:34816
	ds_read_b128 v[38:41], v126 offset:2048
	s_cmp_lt_i32 s6, 2.0
	s_cselect_b32 s11, s43, 0
	s_waitcnt lgkmcnt(0)
	v_mfma_f32_16x16x32_bf16 v[94:97], v[34:37], v[38:41], v[94:97]
	s_cselect_b32 s10, s42, 0
	v_add_u32_e32 v117, s4, v135
	s_lshl_b32 s4, s6, 6
	v_mfma_f32_16x16x32_bf16 v[42:45], v[26:29], v[30:33], v[110:113]
	s_ashr_i32 s5, s4, 31
	s_lshl_b64 s[4:5], s[4:5], 1
	v_add_u32_e32 v13, v139, v141
	v_mfma_f32_16x16x32_bf16 v[46:49], v[26:29], v[38:41], v[102:105]
	s_nop 2
	ds_read_b128 v[102:105], v126 offset:4096
	ds_read_b128 v[110:113], v126 offset:6144
	s_add_u32 s10, s10, s4
	s_addc_u32 s11, s11, s5
	s_waitcnt lgkmcnt(1)
	v_mfma_f32_16x16x32_bf16 v[86:89], v[26:29], v[102:105], v[86:89]
	v_mov_b32_e32 v115, v12
	v_lshl_add_u64 v[132:133], s[10:11], 0, v[114:115]
	s_movk_i32 s3, 0x4000
	s_waitcnt lgkmcnt(0)
	v_mfma_f32_16x16x32_bf16 v[26:29], v[26:29], v[110:113], v[70:73]
	v_add_u32_e32 v127, v138, v141
	v_lshl_add_u32 v162, s8, 7, v134
	v_ashrrev_i32_e32 v163, 31, v162
	v_mfma_f32_16x16x32_bf16 v[70:73], v[34:37], v[30:33], v[106:109]
	s_mov_b32 s8, 0xc000
	s_add_i32 s9, s9, 1
	s_cmp_lg_u32 s9, 4
	ds_read_b128 v[106:109], v121 offset:36864
	v_mfma_f32_16x16x32_bf16 v[78:81], v[34:37], v[102:105], v[78:81]
	v_mfma_f32_16x16x32_bf16 v[128:131], v[34:37], v[110:113], v[62:65]
	ds_read_b128 v[34:37], v121 offset:38912
	s_nop 1
	v_min_i32_e32 v62, 0x407f, v117
	v_ashrrev_i32_e32 v63, 31, v62
	s_waitcnt lgkmcnt(1)
	v_mfma_f32_16x16x32_bf16 v[98:101], v[106:109], v[30:33], v[98:101]
	v_mfma_f32_16x16x32_bf16 v[146:149], v[106:109], v[38:41], v[82:85]
	v_mfma_f32_16x16x32_bf16 v[150:153], v[106:109], v[102:105], v[66:69]
	v_mfma_f32_16x16x32_bf16 v[106:109], v[106:109], v[110:113], v[54:57]
	s_nop 2
	v_lshlrev_b64 v[54:55], 9, v[62:63]
	ds_read_b128 v[62:65], v13 offset:32768
	s_waitcnt lgkmcnt(1)
	v_mfma_f32_16x16x32_bf16 v[154:157], v[34:37], v[30:33], v[90:93]
	v_min_i32_e32 v30, 0x405f, v117
	v_ashrrev_i32_e32 v31, 31, v30
	v_lshlrev_b64 v[30:31], 9, v[30:31]
	v_lshl_add_u64 v[30:31], v[132:133], 0, v[30:31]
	v_add_co_u32_e32 v30, vcc, s3, v30
	v_lshl_add_u64 v[54:55], v[132:133], 0, v[54:55]
	s_nop 0
	v_addc_co_u32_e32 v31, vcc, 0, v31, vcc
	v_mfma_f32_16x16x32_bf16 v[158:161], v[34:37], v[38:41], v[74:77]
	s_mov_b32 s3, 0x8000
	v_mfma_f32_16x16x32_bf16 v[168:171], v[34:37], v[102:105], v[58:61]
	ds_read_b128 v[102:105], v127
	global_load_dwordx4 v[38:41], v[54:55], off
	s_nop 0
	global_load_dwordx4 v[30:33], v[30:31], off
	ds_read_b128 v[82:85], v13 offset:34816
	ds_read_b128 v[180:183], v127 offset:2048
	ds_read_b128 v[202:205], v127 offset:4096
	ds_read_b128 v[206:209], v127 offset:6144
	v_mfma_f32_16x16x32_bf16 v[176:179], v[34:37], v[110:113], v[50:53]
	v_min_i32_e32 v34, 0x403f, v117
	v_ashrrev_i32_e32 v35, 31, v34
	v_lshlrev_b64 v[34:35], 9, v[34:35]
	v_min_i32_e32 v36, 0x401f, v117
	v_lshl_add_u64 v[34:35], v[132:133], 0, v[34:35]
	v_ashrrev_i32_e32 v37, 31, v36
	s_waitcnt lgkmcnt(4)
	v_mfma_f32_16x16x32_bf16 v[50:53], v[62:65], v[102:105], v[42:45]
	v_add_co_u32_e32 v34, vcc, s3, v34
	v_mov_b32_e32 v117, v12
	s_waitcnt lgkmcnt(2)
	v_mfma_f32_16x16x32_bf16 v[54:57], v[62:65], v[180:183], v[46:49]
	v_lshlrev_b64 v[42:43], 9, v[162:163]
	v_addc_co_u32_e32 v35, vcc, 0, v35, vcc
	s_waitcnt lgkmcnt(1)
	v_mfma_f32_16x16x32_bf16 v[58:61], v[62:65], v[202:205], v[86:89]
	v_lshl_add_u64 v[42:43], s[44:45], 0, v[42:43]
	v_lshl_add_u64 v[42:43], v[42:43], 0, s[4:5]
	v_lshl_add_u64 v[42:43], v[42:43], 0, v[116:117]
	s_waitcnt lgkmcnt(0)
	v_mfma_f32_16x16x32_bf16 v[62:65], v[62:65], v[206:209], v[26:29]
	s_waitcnt vmcnt(7)
	v_and_b32_e32 v111, 0xffff0000, v4
	s_waitcnt vmcnt(6)
	v_and_b32_e32 v110, 0xffff0000, v0
	v_lshlrev_b64 v[26:27], 9, v[36:37]
	v_lshl_add_u64 v[26:27], v[132:133], 0, v[26:27]
	v_add_co_u32_e32 v26, vcc, s8, v26
	v_mfma_f32_16x16x32_bf16 v[66:69], v[82:85], v[102:105], v[70:73]
	s_nop 0
	v_addc_co_u32_e32 v27, vcc, 0, v27, vcc
	v_add_co_u32_e32 v44, vcc, s3, v42
	global_load_dwordx4 v[34:37], v[34:35], off
	s_nop 0
	global_load_dwordx4 v[26:29], v[26:27], off
	v_addc_co_u32_e32 v45, vcc, 0, v43, vcc
	v_mfma_f32_16x16x32_bf16 v[70:73], v[82:85], v[180:183], v[94:97]
	v_mul_f32_e64 v132, v110, v110
	v_mul_f32_e64 v133, v111, v111
	v_mfma_f32_16x16x32_bf16 v[74:77], v[82:85], v[202:205], v[78:81]
	ds_read_b128 v[94:97], v13 offset:36864
	v_mfma_f32_16x16x32_bf16 v[78:81], v[82:85], v[206:209], v[128:131]
	s_nop 2
	ds_read_b128 v[128:131], v13 offset:38912
	global_load_dwordx4 v[46:49], v[42:43], off
	s_nop 0
	global_load_dwordx4 v[42:45], v[44:45], off
	s_waitcnt lgkmcnt(1)
;     ...
;     auto store = [&](const u32x4 (&ra)[4], const u32x4 (&rb)[2], const u32x4& rx, int buf) {
; #pragma unroll
;       for (int i = 0; i < 4; ++i) {
;         if (RS) ss[i] += sumsq8(__builtin_bit_cast(bf16x8, ra[i]));
;         *(u32x4*)(As + buf * ASTG + i * 4096 + soff) = ra[i];
;       }
; #pragma unroll
;       for (int i = 0; i < 2; ++i) *(u32x4*)(Bs + buf * 16384 + i * 8192 + woff) = rb[i];
;       if (TI == 5) {
;         if (RS) ss[4] += sumsq8(__builtin_bit_cast(bf16x8, rx));
;         if (srow == 0) *(u32x4*)(Ax0 + buf * 128 + ((tid & 7) << 4)) = rx;
;       }
;       if (RS) {
;         if (++st_kt == nk) {
;           st_kt = 0;
; #pragma unroll
;           for (int i = 0; i < TI; ++i) {
;             float t = ss[i];
;             t += __shfl_xor(t, 1); t += __shfl_xor(t, 2); t += __shfl_xor(t, 4);
;             if ((tid & 7) == 0 && i < 4) rsl[srow + 32 * i] = rsqrtf(t * invK + EPS_);
;             ss[i] = 0.f;
;           }
;         }
;       }
	v_mfma_f32_16x16x32_bf16 v[82:85], v[94:97], v[102:105], v[98:101]
	ds_write_b128 v137, v[4:7] offset:16384
	ds_write_b128 v137, v[0:3] offset:20480
	s_waitcnt vmcnt(9)
	ds_write_b128 v137, v[14:17] offset:24576
	v_lshlrev_b32_e32 v101, 16, v4
	v_lshlrev_b32_e32 v100, 16, v0
	v_and_b32_e32 v99, 0xffff0000, v5
	v_mfma_f32_16x16x32_bf16 v[86:89], v[94:97], v[180:183], v[146:149]
	v_lshlrev_b32_e32 v5, 16, v5
	v_lshlrev_b32_e32 v4, 16, v1
	v_and_b32_e32 v98, 0xffff0000, v1
	v_mfma_f32_16x16x32_bf16 v[90:93], v[94:97], v[202:205], v[150:153]
	v_and_b32_e32 v1, 0xffff0000, v15
	s_waitcnt vmcnt(8)
	v_and_b32_e32 v0, 0xffff0000, v9
	ds_write_b128 v137, v[8:11] offset:28672
	s_waitcnt vmcnt(7)
	ds_write_b128 v136, v[22:25] offset:49152
	v_mfma_f32_16x16x32_bf16 v[110:113], v[94:97], v[206:209], v[106:109]
	v_fma_f32 v94, v100, v100, v132
	v_fma_f32 v95, v101, v101, v133
	s_waitcnt vmcnt(6)
	ds_write_b128 v136, v[18:21] offset:57344
	v_fma_f32 v4, v4, v4, v94
	v_fma_f32 v5, v5, v5, v95
	v_lshlrev_b32_e32 v95, 16, v6
	v_fma_f32 v4, v98, v98, v4
	v_fma_f32 v5, v99, v99, v5
	v_lshlrev_b32_e32 v94, 16, v2
	v_fma_f32 v4, v94, v94, v4
	v_fma_f32 v5, v95, v95, v5
	v_and_b32_e32 v99, 0xffff0000, v6
	v_and_b32_e32 v98, 0xffff0000, v2
	s_waitcnt lgkmcnt(6)
	v_mfma_f32_16x16x32_bf16 v[102:105], v[128:131], v[102:105], v[154:157]
	v_fma_f32 v4, v98, v98, v4
	v_fma_f32 v5, v99, v99, v5
	v_and_b32_e32 v6, 0xffff0000, v3
	v_lshlrev_b32_e32 v2, 16, v8
	v_mfma_f32_16x16x32_bf16 v[106:109], v[128:131], v[180:183], v[158:161]
	v_mfma_f32_16x16x32_bf16 v[94:97], v[128:131], v[202:205], v[168:171]
	v_mfma_f32_16x16x32_bf16 v[98:101], v[128:131], v[206:209], v[176:179]
	v_lshlrev_b32_e32 v129, 16, v7
	v_lshlrev_b32_e32 v128, 16, v3
	v_fma_f32 v4, v128, v128, v4
	v_fma_f32 v5, v129, v129, v5
	v_and_b32_e32 v7, 0xffff0000, v7
	v_fma_f32 v4, v6, v6, v4
	v_fma_f32 v5, v7, v7, v5
	v_lshlrev_b32_e32 v3, 16, v14
	v_add_f32_e32 v124, v124, v4
	v_add_f32_e32 v125, v125, v5
	v_and_b32_e32 v5, 0xffff0000, v14
	v_and_b32_e32 v4, 0xffff0000, v8
	v_mul_f32_e32 v4, v4, v4
	v_mul_f32_e32 v5, v5, v5
	v_lshlrev_b32_e32 v7, 16, v15
	v_lshlrev_b32_e32 v6, 16, v9
	v_fma_f32 v2, v2, v2, v4
	v_fma_f32 v3, v3, v3, v5
	s_nop 0
	v_fma_f32 v2, v6, v6, v2
	v_fma_f32 v3, v7, v7, v3
	s_nop 0
	v_fma_f32 v0, v0, v0, v2
	v_fma_f32 v1, v1, v1, v3
	v_lshlrev_b32_e32 v3, 16, v16
	v_lshlrev_b32_e32 v2, 16, v10
	v_fma_f32 v0, v2, v2, v0
	v_fma_f32 v1, v3, v3, v1
	v_and_b32_e32 v3, 0xffff0000, v16
	v_and_b32_e32 v2, 0xffff0000, v10
	v_fma_f32 v0, v2, v2, v0
	v_fma_f32 v1, v3, v3, v1
	v_lshlrev_b32_e32 v3, 16, v17
	v_lshlrev_b32_e32 v2, 16, v11
	v_fma_f32 v0, v2, v2, v0
	v_fma_f32 v1, v3, v3, v1
	v_and_b32_e32 v3, 0xffff0000, v17
	v_and_b32_e32 v2, 0xffff0000, v11
	v_fma_f32 v0, v2, v2, v0
	v_fma_f32 v1, v3, v3, v1
	s_nop 0
	v_add_f32_e32 v122, v122, v0
	v_add_f32_e32 v123, v123, v1
	s_cbranch_scc1 .LBB0_760
	v_and_b32_e32 v1, 64, v191
	v_xor_b32_e32 v0, 1, v191
	v_add_u32_e32 v2, 64, v1
	v_cmp_lt_i32_e32 vcc, v0, v2
	v_xor_b32_e32 v1, 2, v191
	v_xor_b32_e32 v5, 4, v191
	v_cndmask_b32_e32 v0, v191, v0, vcc
	v_lshlrev_b32_e32 v0, 2, v0
	ds_bpermute_b32 v3, v0, v125
	v_cmp_lt_i32_e32 vcc, v1, v2
	s_waitcnt lgkmcnt(0)
	v_add_f32_e32 v3, v125, v3
	v_cndmask_b32_e32 v1, v191, v1, vcc
	v_lshlrev_b32_e32 v1, 2, v1
	ds_bpermute_b32 v4, v1, v3
	v_cmp_lt_i32_e32 vcc, v5, v2
	s_waitcnt lgkmcnt(0)
	v_add_f32_e32 v3, v3, v4
	v_cndmask_b32_e32 v2, v191, v5, vcc
	v_lshlrev_b32_e32 v2, 2, v2
	ds_bpermute_b32 v4, v2, v3
	s_and_saveexec_b64 s[4:5], s[38:39]
	s_cbranch_execz .LBB0_753
	s_waitcnt lgkmcnt(0)
	v_add_f32_e32 v3, v3, v4
	v_fmamk_f32 v3, v3, 0x3b800000, v187
	v_mul_f32_e32 v4, 0x4b800000, v3
	v_cmp_gt_f32_e32 vcc, s33, v3
	s_nop 1
	v_cndmask_b32_e32 v3, v3, v4, vcc
	v_rsq_f32_e32 v3, v3
	s_nop 0
	v_mul_f32_e32 v4, 0x45800000, v3
	v_cndmask_b32_e32 v3, v3, v4, vcc
	ds_write_b32 v142, v3

;     ...
;     auto store = [&](const u32x4 (&ra)[4], const u32x4 (&rb)[2], const u32x4& rx, int buf) {
; #pragma unroll
;       for (int i = 0; i < 4; ++i) {
;         if (RS) ss[i] += sumsq8(__builtin_bit_cast(bf16x8, ra[i]));
;         *(u32x4*)(As + buf * ASTG + i * 4096 + soff) = ra[i];
;       }
; #pragma unroll
;       for (int i = 0; i < 2; ++i) *(u32x4*)(Bs + buf * 16384 + i * 8192 + woff) = rb[i];
;       if (TI == 5) {
;         if (RS) ss[4] += sumsq8(__builtin_bit_cast(bf16x8, rx));
;         if (srow == 0) *(u32x4*)(Ax0 + buf * 128 + ((tid & 7) << 4)) = rx;
;       }
;       if (RS) {
;         if (++st_kt == nk) {
;           st_kt = 0;
; #pragma unroll
;           for (int i = 0; i < TI; ++i) {
;             float t = ss[i];
;             t += __shfl_xor(t, 1); t += __shfl_xor(t, 2); t += __shfl_xor(t, 4);
;             if ((tid & 7) == 0 && i < 4) rsl[srow + 32 * i] = rsqrtf(t * invK + EPS_);
;             ss[i] = 0.f;
;           }
;         }
;       }
.LBB0_776:
	s_waitcnt vmcnt(11)
	v_and_b32_e32 v129, 0xffff0000, v38
	s_waitcnt vmcnt(10)
	v_and_b32_e32 v128, 0xffff0000, v30
	v_lshlrev_b32_e32 v127, 16, v38
	v_lshlrev_b32_e32 v126, 16, v30
	v_mul_f32_e32 v128, v128, v128
	v_mul_f32_e32 v129, v129, v129
	ds_write_b128 v137, v[38:41]
	v_fma_f32 v126, v126, v126, v128
	v_fma_f32 v127, v127, v127, v129
	v_lshlrev_b32_e32 v129, 16, v39
	v_lshlrev_b32_e32 v128, 16, v31
	v_fma_f32 v126, v128, v128, v126
	v_fma_f32 v127, v129, v129, v127
	v_and_b32_e32 v39, 0xffff0000, v39
	v_and_b32_e32 v38, 0xffff0000, v31
	v_fma_f32 v38, v38, v38, v126
	v_fma_f32 v39, v39, v39, v127
	v_lshlrev_b32_e32 v127, 16, v40
	v_lshlrev_b32_e32 v126, 16, v32
	v_fma_f32 v38, v126, v126, v38
	v_fma_f32 v39, v127, v127, v39
	v_and_b32_e32 v127, 0xffff0000, v40
	v_and_b32_e32 v126, 0xffff0000, v32
	v_fma_f32 v38, v126, v126, v38
	v_fma_f32 v39, v127, v127, v39
	v_lshlrev_b32_e32 v126, 16, v33
	v_and_b32_e32 v40, 0xffff0000, v33
	ds_write_b128 v137, v[30:33] offset:4096
	s_waitcnt vmcnt(9)
	ds_write_b128 v137, v[34:37] offset:8192
	v_and_b32_e32 v33, 0xffff0000, v34
	s_waitcnt vmcnt(8)
	v_and_b32_e32 v32, 0xffff0000, v26
	v_lshlrev_b32_e32 v31, 16, v34
	v_lshlrev_b32_e32 v30, 16, v26
	v_mul_f32_e32 v32, v32, v32
	v_mul_f32_e32 v33, v33, v33
	v_lshlrev_b32_e32 v127, 16, v41
	v_fma_f32 v30, v30, v30, v32
	v_fma_f32 v31, v31, v31, v33
	v_lshlrev_b32_e32 v33, 16, v35
	v_lshlrev_b32_e32 v32, 16, v27
	v_fma_f32 v30, v32, v32, v30
	v_fma_f32 v31, v33, v33, v31
	v_and_b32_e32 v33, 0xffff0000, v35
	v_and_b32_e32 v32, 0xffff0000, v27
	v_fma_f32 v30, v32, v32, v30
	v_fma_f32 v31, v33, v33, v31
	v_lshlrev_b32_e32 v33, 16, v36
	v_lshlrev_b32_e32 v32, 16, v28
	v_fma_f32 v30, v32, v32, v30
	v_fma_f32 v31, v33, v33, v31
	v_and_b32_e32 v33, 0xffff0000, v36
	v_and_b32_e32 v32, 0xffff0000, v28
	v_fma_f32 v30, v32, v32, v30
	v_fma_f32 v31, v33, v33, v31
	v_lshlrev_b32_e32 v33, 16, v37
	v_lshlrev_b32_e32 v32, 16, v29
	v_fma_f32 v38, v126, v126, v38
	v_fma_f32 v39, v127, v127, v39
	v_and_b32_e32 v41, 0xffff0000, v41
	v_fma_f32 v30, v32, v32, v30
	v_fma_f32 v31, v33, v33, v31
	v_and_b32_e32 v33, 0xffff0000, v37
	v_and_b32_e32 v32, 0xffff0000, v29
	v_fma_f32 v38, v40, v40, v38
	v_fma_f32 v39, v41, v41, v39
	v_fma_f32 v30, v32, v32, v30
	v_fma_f32 v31, v33, v33, v31
	s_add_i32 s9, s9, 1
	v_pk_add_f32 v[124:125], v[38:39], v[124:125]
	v_pk_add_f32 v[122:123], v[30:31], v[122:123]
	s_cmp_lg_u32 s9, 4
	ds_write_b128 v137, v[26:29] offset:12288
	s_waitcnt vmcnt(7)
	ds_write_b128 v136, v[46:49] offset:32768
	s_waitcnt vmcnt(6)
	ds_write_b128 v136, v[42:45] offset:40960
	s_cbranch_scc1 .LBB0_745
	v_and_b32_e32 v26, 64, v191
	v_xor_b32_e32 v13, 1, v191
	v_add_u32_e32 v27, 64, v26
	v_cmp_lt_i32_e32 vcc, v13, v27
	v_xor_b32_e32 v26, 2, v191
	v_xor_b32_e32 v30, 4, v191
	v_cndmask_b32_e32 v13, v191, v13, vcc
	v_lshlrev_b32_e32 v13, 2, v13
	ds_bpermute_b32 v28, v13, v125
	v_cmp_lt_i32_e32 vcc, v26, v27
	s_waitcnt lgkmcnt(0)
	v_add_f32_e32 v28, v125, v28
	v_cndmask_b32_e32 v26, v191, v26, vcc
	v_lshlrev_b32_e32 v26, 2, v26
	ds_bpermute_b32 v29, v26, v28
	v_cmp_lt_i32_e32 vcc, v30, v27
	s_waitcnt lgkmcnt(0)
	v_add_f32_e32 v28, v28, v29
	v_cndmask_b32_e32 v27, v191, v30, vcc
	v_lshlrev_b32_e32 v27, 2, v27
	ds_bpermute_b32 v29, v27, v28
	s_and_saveexec_b64 s[4:5], s[38:39]
	s_cbranch_execz .LBB0_779
	s_waitcnt lgkmcnt(0)
	v_add_f32_e32 v28, v28, v29
	v_fmamk_f32 v28, v28, 0x3b800000, v187
	v_mul_f32_e32 v29, 0x4b800000, v28
	v_cmp_gt_f32_e32 vcc, s33, v28
	s_nop 1
	v_cndmask_b32_e32 v28, v28, v29, vcc
	v_rsq_f32_e32 v28, v28
	s_nop 0
	v_mul_f32_e32 v29, 0x45800000, v28
	v_cndmask_b32_e32 v28, v28, v29, vcc
	ds_write_b32 v142, v28
